# cross-attention: K/V tiles 1..3 handed to LDS behind counted waits + a barrier just before their first read (load time overlaps the previous tile's compute)
# baseline (speedup 1.0000x reference)
.LBB0_902:
	s_and_b32 s8, s14, 3
	s_mul_i32 s6, s0, 0x120000
	s_mul_hi_i32 s3, s0, 0x120000
	s_add_u32 s6, s92, s6
	s_addc_u32 s3, s93, s3
	s_lshl_b32 s15, s8, 7
	s_add_u32 s18, s6, s15
	s_addc_u32 s19, s3, 0
	s_ashr_i32 s3, s2, 31
	s_lshl_b64 s[6:7], s[2:3], 17
	s_add_u32 s3, s10, s6
	s_addc_u32 s7, s11, s7
	s_add_u32 s6, s3, s15
	s_addc_u32 s7, s7, 0
	s_lshl_b32 s2, s2, 2
	s_or_b32 s2, s2, s8
	s_ashr_i32 s3, s2, 31
	s_lshl_b64 s[2:3], s[2:3], 15
	s_add_u32 s8, s12, s2
	s_addc_u32 s9, s13, s3
	s_lshl_b64 s[0:1], s[0:1], 19
	s_add_u32 s0, s94, s0
	s_addc_u32 s1, s95, s1
	s_add_u32 s0, s0, s15
	v_mov_b32_e32 v34, v250
	s_addc_u32 s1, s1, 0
	s_add_u32 s2, s18, 0x1000
	v_ashrrev_i32_e32 v0, 1, v34
	v_bfe_u32 v58, v34, 5, 1
	s_waitcnt vmcnt(0)
	v_bfi_b32 v98, s88, v0, v34
	v_mov_b64_e32 v[0:1], s[18:19]
	s_addc_u32 s3, s19, 0
	v_mad_i64_i32 v[0:1], s[18:19], v98, s33, v[0:1]
	v_lshlrev_b32_e32 v176, 4, v58
	v_lshl_add_u64 v[0:1], v[0:1], 0, v[176:177]
	global_load_dwordx4 v[94:97], v[0:1], off offset:3584
	global_load_dwordx4 v[90:93], v[0:1], off offset:3616
	global_load_dwordx4 v[86:89], v[0:1], off offset:3648
	global_load_dwordx4 v[82:85], v[0:1], off offset:3680
	v_ashrrev_i32_e32 v32, 3, v34
	v_lshlrev_b32_e32 v0, 4, v34
	v_and_b32_e32 v4, 0x70, v0
	v_mov_b32_e32 v5, v177
	v_ashrrev_i32_e32 v33, 31, v32
	v_xor_b32_e32 v37, v0, v34
	v_lshl_add_u64 v[0:1], s[6:7], 0, v[4:5]
	v_lshlrev_b64 v[2:3], 9, v[32:33]
	v_lshl_add_u64 v[24:25], v[0:1], 0, v[2:3]
	s_mov_b32 s6, 0x8000
	v_add_co_u32_e32 v8, vcc, s6, v24
	s_mov_b32 s6, 0x10000
	s_nop 0
	v_addc_co_u32_e32 v9, vcc, 0, v25, vcc
	v_lshl_add_u64 v[6:7], s[8:9], 0, v[2:3]
	v_add_co_u32_e32 v16, vcc, s6, v24
	v_lshl_add_u64 v[28:29], v[6:7], 0, v[4:5]
	s_nop 0
	v_addc_co_u32_e32 v17, vcc, 0, v25, vcc
	s_mov_b32 s6, 0x18000
	global_load_dwordx4 v[0:3], v[24:25], off
	global_load_dwordx4 v[4:7], v[28:29], off
	v_add_co_u32_e32 v24, vcc, s6, v24
	global_load_dwordx4 v[180:183], v[8:9], off
	s_nop 0
	global_load_dwordx4 v[184:187], v[28:29], off offset:128
	v_addc_co_u32_e32 v25, vcc, 0, v25, vcc
	global_load_dwordx4 v[188:191], v[16:17], off
	s_nop 0
	global_load_dwordx4 v[192:195], v[28:29], off offset:256
	s_nop 0
	global_load_dwordx4 v[196:199], v[24:25], off
	s_nop 0
	global_load_dwordx4 v[200:203], v[28:29], off offset:384
	v_lshlrev_b32_e32 v32, 7, v32
	s_movk_i32 s6, 0x70
	v_and_or_b32 v32, v37, s6, v32
	v_mov_b32_e32 v204, v32
	s_waitcnt lgkmcnt(0)
	s_barrier
	v_and_b32_e32 v35, 31, v34
	v_lshrrev_b32_e32 v36, 5, v34
	v_bfe_u32 v59, v34, 1, 3
	v_lshlrev_b32_e32 v60, 7, v35
	v_bitop3_b32 v36, v36, v59, 1 bitop3:0x6c
	v_lshl_or_b32 v163, v36, 4, v60
	v_ashrrev_i32_e32 v99, 31, v98
	s_add_i32 s14, s14, s90
	s_cmpk_gt_i32 s14, 0x2ff
	s_waitcnt vmcnt(7)
	ds_write_b128 v32, v[0:3]
	s_waitcnt vmcnt(6)
	ds_write_b128 v32, v[4:7] offset:8192
	v_mov_b64_e32 v[178:179], s[2:3]
	v_mad_i64_i32 v[178:179], s[2:3], v98, s33, v[178:179]
	v_lshl_add_u64 v[178:179], v[178:179], 0, v[176:177]
	v_lshlrev_b32_e32 v1, 1, v34
	v_lshrrev_b32_e32 v2, 1, v34
	v_and_b32_e32 v0, 19, v34
	v_and_b32_e32 v1, 8, v1
	v_and_b32_e32 v2, 4, v2
	v_or3_b32 v0, v1, v0, v2
	v_lshrrev_b32_e32 v37, 1, v0
	v_lshlrev_b32_e32 v38, 7, v0
	v_bitop3_b32 v0, v37, v58, 7 bitop3:0x6c
	v_lshl_or_b32 v103, v0, 4, v38
	s_waitcnt lgkmcnt(0)
	s_barrier
	ds_read_b128 v[0:3], v103
	ds_read_b128 v[16:19], v103 offset:4096
	v_or_b32_e32 v32, 2, v58
	v_bitop3_b32 v32, v37, v32, 7 bitop3:0x6c
	v_lshl_or_b32 v105, v32, 4, v38
	ds_read_b128 v[32:35], v105
	s_waitcnt lgkmcnt(2)
	v_mfma_f32_32x32x16_bf16 v[0:15], v[0:3], v[94:97], 0
	ds_read_b128 v[150:153], v163 offset:12288
	s_mov_b32 s2, 0xf149f2ca
	s_waitcnt lgkmcnt(1)
	v_mfma_f32_32x32x16_bf16 v[0:15], v[32:35], v[90:93], v[0:15]
	ds_read_b128 v[32:35], v105 offset:4096
	v_mfma_f32_32x32x16_bf16 v[16:31], v[16:19], v[94:97], 0
	s_waitcnt lgkmcnt(0)
	v_mfma_f32_32x32x16_bf16 v[16:31], v[32:35], v[90:93], v[16:31]
	global_load_dwordx4 v[78:81], v[178:179], off
	v_or_b32_e32 v32, 4, v58
	v_bitop3_b32 v32, v37, v32, 7 bitop3:0x6c
	v_lshl_or_b32 v107, v32, 4, v38
	ds_read_b128 v[32:35], v107
	s_waitcnt lgkmcnt(0)
	v_mfma_f32_32x32x16_bf16 v[0:15], v[32:35], v[86:89], v[0:15]
	ds_read_b128 v[32:35], v107 offset:4096
	s_waitcnt lgkmcnt(0)
	v_mfma_f32_32x32x16_bf16 v[16:31], v[32:35], v[86:89], v[16:31]
	v_or_b32_e32 v32, 6, v58
	v_bitop3_b32 v32, v37, v32, 7 bitop3:0x6c
	v_lshl_or_b32 v101, v32, 4, v38
	ds_read_b128 v[32:35], v101
	s_waitcnt lgkmcnt(0)
	v_mfma_f32_32x32x16_bf16 v[0:15], v[32:35], v[82:85], v[0:15]
	ds_read_b128 v[32:35], v101 offset:4096
	s_waitcnt lgkmcnt(0)
	v_mfma_f32_32x32x16_bf16 v[16:31], v[32:35], v[82:85], v[16:31]
	s_nop 8
	v_max_f32_e32 v32, v1, v1
	v_max_f32_e32 v33, v0, v0
	v_max_f32_e32 v32, v33, v32
	v_max3_f32 v32, v32, v2, v3
	v_max3_f32 v32, v32, v4, v5
	v_max3_f32 v32, v32, v6, v7
	v_max3_f32 v32, v32, v8, v9
	v_max3_f32 v32, v32, v10, v11
	v_max3_f32 v32, v32, v12, v13
	v_max3_f32 v32, v32, v14, v15
	v_max3_f32 v32, v32, v16, v17
	v_max3_f32 v32, v32, v18, v19
	v_max3_f32 v32, v32, v20, v21
	v_max3_f32 v32, v32, v22, v23
	v_max3_f32 v32, v32, v24, v25
	v_max3_f32 v32, v32, v26, v27
	v_max3_f32 v32, v32, v28, v29
	v_max3_f32 v32, v32, v30, v31
	v_mov_b32_e32 v33, v32
	s_nop 1
	v_permlane32_swap_b32_e32 v32, v33
	v_max3_f32 v109, v32, v33, s2
	v_sub_f32_e32 v0, v0, v109
	v_exp_f32_e32 v38, v0
	v_sub_f32_e32 v0, v16, v109
	v_exp_f32_e32 v39, v0
	v_sub_f32_e32 v37, 0xf149f2ca, v109
	v_add_f32_e32 v0, v38, v39
	v_add_f32_e32 v33, 0, v0
	v_sub_f32_e32 v0, v1, v109
	v_exp_f32_e32 v40, v0
	v_sub_f32_e32 v0, v17, v109
	v_exp_f32_e32 v41, v0
	v_sub_f32_e32 v0, v2, v109
	v_exp_f32_e32 v16, v0
	v_sub_f32_e32 v0, v18, v109
	v_exp_f32_e32 v32, v0
	v_add_f32_e32 v17, v40, v41
	v_cvt_pk_bf16_f32 v62, v38, v40
	v_cvt_pk_bf16_f32 v54, v39, v41
	v_add_f32_e32 v0, v16, v32
	v_add_f32_e32 v1, v17, v33
	s_nop 0
	v_add_f32_e32 v34, v0, v0
	v_add_f32_e32 v35, v0, v1
	v_sub_f32_e32 v0, v3, v109
	v_exp_f32_e32 v17, v0
	v_sub_f32_e32 v0, v19, v109
	v_exp_f32_e32 v33, v0
	v_sub_f32_e32 v0, v4, v109
	v_exp_f32_e32 v18, v0
	v_sub_f32_e32 v0, v20, v109
	v_exp_f32_e32 v34, v0
	v_add_f32_e32 v19, v17, v33
	v_cvt_pk_bf16_f32 v63, v16, v17
	v_cvt_pk_bf16_f32 v55, v32, v33
	v_add_f32_e32 v0, v18, v34
	v_add_f32_e32 v1, v19, v35
	s_nop 0
	v_add_f32_e32 v144, v0, v1
	v_add_f32_e32 v145, v1, v0
	v_sub_f32_e32 v0, v5, v109
	v_exp_f32_e32 v104, v0
	v_sub_f32_e32 v0, v21, v109
	v_exp_f32_e32 v100, v0
	v_sub_f32_e32 v0, v6, v109
	v_exp_f32_e32 v108, v0
	v_sub_f32_e32 v0, v22, v109
	v_exp_f32_e32 v102, v0
	v_sub_f32_e32 v0, v7, v109
	v_exp_f32_e32 v112, v0
	v_sub_f32_e32 v0, v23, v109
	v_exp_f32_e32 v106, v0
	v_sub_f32_e32 v0, v8, v109
	v_exp_f32_e32 v116, v0
	v_sub_f32_e32 v0, v24, v109
	v_exp_f32_e32 v110, v0
	v_sub_f32_e32 v0, v9, v109
	v_exp_f32_e32 v120, v0
	v_sub_f32_e32 v0, v25, v109
	v_exp_f32_e32 v114, v0
	v_sub_f32_e32 v0, v10, v109
	v_exp_f32_e32 v122, v0
	v_sub_f32_e32 v0, v26, v109
	v_exp_f32_e32 v118, v0
	v_sub_f32_e32 v0, v11, v109
	v_exp_f32_e32 v128, v0
	v_sub_f32_e32 v0, v27, v109
	v_exp_f32_e32 v124, v0
	v_sub_f32_e32 v0, v12, v109
	v_exp_f32_e32 v132, v0
	v_sub_f32_e32 v0, v28, v109
	v_exp_f32_e32 v126, v0
	v_sub_f32_e32 v0, v13, v109
	v_exp_f32_e32 v136, v0
	v_sub_f32_e32 v0, v29, v109
	v_exp_f32_e32 v130, v0
	v_sub_f32_e32 v0, v14, v109
	v_exp_f32_e32 v140, v0
	v_sub_f32_e32 v0, v30, v109
	v_exp_f32_e32 v134, v0
	v_sub_f32_e32 v0, v15, v109
	v_exp_f32_e32 v142, v0
	v_sub_f32_e32 v0, v31, v109
	v_exp_f32_e32 v138, v0
	v_exp_f32_e32 v0, v37
	v_cvt_pk_bf16_f32 v56, v34, v100
	ds_read_b128 v[34:37], v163 offset:8192
	v_cvt_pk_bf16_f32 v64, v18, v104
	v_mul_f32_e32 v0, 0, v0
	v_mov_b32_e32 v1, v0
	v_mov_b32_e32 v2, v0
	v_mov_b32_e32 v3, v0
	v_mov_b32_e32 v4, v0
	v_mov_b32_e32 v5, v0
	v_mov_b32_e32 v6, v0
	v_mov_b32_e32 v7, v0
	v_mov_b32_e32 v8, v0
	v_mov_b32_e32 v9, v0
	v_mov_b32_e32 v10, v0
	v_mov_b32_e32 v11, v0
	v_mov_b32_e32 v12, v0
	v_mov_b32_e32 v13, v0
	v_mov_b32_e32 v14, v0
	v_mov_b32_e32 v15, v0
	v_cvt_pk_bf16_f32 v65, v108, v112
	v_cvt_pk_bf16_f32 v146, v116, v120
	v_cvt_pk_bf16_f32 v147, v122, v128
	s_waitcnt lgkmcnt(0)
	v_mfma_f32_32x32x16_bf16 v[18:33], v[34:37], v[62:65], v[0:15]
	v_mov_b64_e32 v[48:49], v[14:15]
	v_mov_b64_e32 v[46:47], v[12:13]
	v_mov_b64_e32 v[44:45], v[10:11]
	v_mov_b64_e32 v[42:43], v[8:9]
	v_mov_b64_e32 v[40:41], v[6:7]
	v_mov_b64_e32 v[38:39], v[4:5]
	v_mov_b64_e32 v[36:37], v[2:3]
	v_mov_b64_e32 v[34:35], v[0:1]
	v_bitop3_b32 v1, v58, v59, 2 bitop3:0x36
	v_lshl_or_b32 v162, v1, 4, v60
	ds_read_b128 v[2:5], v162 offset:8192
	v_cvt_pk_bf16_f32 v148, v132, v136
	v_cvt_pk_bf16_f32 v149, v140, v142
	v_mfma_f32_32x32x16_bf16 v[34:49], v[150:153], v[62:65], v[34:49]
	v_bitop3_b32 v1, v58, v59, 4 bitop3:0x36
	v_lshl_or_b32 v161, v1, 4, v60
	v_cvt_pk_bf16_f32 v57, v102, v106
	v_bitop3_b32 v1, v58, v59, 6 bitop3:0x36
	v_lshl_or_b32 v160, v1, 4, v60
	v_cvt_pk_bf16_f32 v50, v110, v114
	v_cvt_pk_bf16_f32 v51, v118, v124
	s_waitcnt lgkmcnt(0)
	v_mfma_f32_32x32x16_bf16 v[18:33], v[2:5], v[146:149], v[18:33]
	ds_read_b128 v[2:5], v162 offset:12288
	v_cvt_pk_bf16_f32 v52, v126, v130
	v_cvt_pk_bf16_f32 v53, v134, v138
	v_mov_b32_e32 v145, v177
	s_waitcnt lgkmcnt(0)
	v_mfma_f32_32x32x16_bf16 v[34:49], v[2:5], v[146:149], v[34:49]
	ds_read_b128 v[2:5], v161 offset:8192
	s_waitcnt vmcnt(6)
	ds_write_b128 v204, v[180:183] offset:16384
	s_waitcnt vmcnt(5)
	ds_write_b128 v204, v[184:187] offset:24576
	s_waitcnt lgkmcnt(0)
	s_barrier
	ds_read_b128 v[146:149], v105 offset:16384
	s_waitcnt lgkmcnt(1)
	v_mfma_f32_32x32x16_bf16 v[18:33], v[2:5], v[54:57], v[18:33]
	ds_read_b128 v[2:5], v161 offset:12288
	s_waitcnt lgkmcnt(0)
	v_mfma_f32_32x32x16_bf16 v[34:49], v[2:5], v[54:57], v[34:49]
	global_load_dwordx4 v[74:77], v[178:179], off offset:32
	ds_read_b128 v[2:5], v160 offset:8192
	s_waitcnt lgkmcnt(0)
	v_mfma_f32_32x32x16_bf16 v[18:33], v[2:5], v[50:53], v[18:33]
	ds_read_b128 v[2:5], v160 offset:12288
	s_waitcnt lgkmcnt(0)
	v_mfma_f32_32x32x16_bf16 v[34:49], v[2:5], v[50:53], v[34:49]
	ds_read_b128 v[2:5], v103 offset:16384
	ds_read_b128 v[50:53], v103 offset:20480
	s_waitcnt lgkmcnt(1)
	v_mfma_f32_32x32x16_bf16 v[2:17], v[2:5], v[94:97], 0
	v_mfma_f32_32x32x16_bf16 v[2:17], v[146:149], v[90:93], v[2:17]
	ds_read_b128 v[146:149], v105 offset:20480
	s_waitcnt lgkmcnt(1)
	v_mfma_f32_32x32x16_bf16 v[50:65], v[50:53], v[94:97], 0
	s_waitcnt lgkmcnt(0)
	v_mfma_f32_32x32x16_bf16 v[50:65], v[146:149], v[90:93], v[50:65]
	ds_read_b128 v[146:149], v107 offset:16384
	s_waitcnt lgkmcnt(0)
	v_mfma_f32_32x32x16_bf16 v[2:17], v[146:149], v[86:89], v[2:17]
	ds_read_b128 v[146:149], v107 offset:20480
	s_waitcnt lgkmcnt(0)
	v_mfma_f32_32x32x16_bf16 v[50:65], v[146:149], v[86:89], v[50:65]
	ds_read_b128 v[146:149], v101 offset:16384
	s_waitcnt lgkmcnt(0)
	v_mfma_f32_32x32x16_bf16 v[2:17], v[146:149], v[82:85], v[2:17]
	ds_read_b128 v[146:149], v101 offset:20480
	s_waitcnt lgkmcnt(0)
	v_mfma_f32_32x32x16_bf16 v[50:65], v[146:149], v[82:85], v[50:65]
	s_nop 8
	v_max_f32_e32 v1, v3, v3
	v_max_f32_e32 v111, v2, v2
	v_max_f32_e32 v1, v111, v1
	v_max3_f32 v1, v1, v4, v5
	v_max3_f32 v1, v1, v6, v7
	v_max3_f32 v1, v1, v8, v9
	v_max3_f32 v1, v1, v10, v11
	v_max3_f32 v1, v1, v12, v13
	v_max3_f32 v1, v1, v14, v15
	v_max3_f32 v1, v1, v16, v17
	v_max3_f32 v1, v1, v50, v51
	v_max3_f32 v1, v1, v52, v53
	v_max3_f32 v1, v1, v54, v55
	v_max3_f32 v1, v1, v56, v57
	v_max3_f32 v1, v1, v58, v59
	v_max3_f32 v1, v1, v60, v61
	v_max3_f32 v1, v1, v62, v63
	v_max3_f32 v1, v1, v64, v65
	v_mov_b32_e32 v111, v1
	s_nop 1
	v_permlane32_swap_b32_e32 v1, v111
	v_max3_f32 v1, v109, v1, v111
	v_sub_f32_e32 v2, v2, v1
	v_exp_f32_e32 v111, v2
	v_sub_f32_e32 v2, v50, v1
	v_exp_f32_e32 v113, v2
	v_sub_f32_e32 v109, v109, v1
	v_exp_f32_e32 v150, v109
	v_add_f32_e32 v2, v111, v113
	v_add_f32_e32 v153, 0, v2
	v_sub_f32_e32 v2, v3, v1
	v_exp_f32_e32 v115, v2
	v_sub_f32_e32 v2, v51, v1
	v_exp_f32_e32 v117, v2
	v_sub_f32_e32 v2, v4, v1
	v_exp_f32_e32 v50, v2
	v_sub_f32_e32 v2, v52, v1
	v_exp_f32_e32 v152, v2
	v_add_f32_e32 v51, v115, v117
	v_add_f32_e32 v2, v50, v152
	v_add_f32_e32 v3, v51, v153
	s_nop 0
	v_add_f32_e32 v154, v2, v2
	v_add_f32_e32 v155, v2, v3
	v_sub_f32_e32 v2, v5, v1
	v_exp_f32_e32 v51, v2
	v_sub_f32_e32 v2, v53, v1
	v_exp_f32_e32 v119, v2
	v_sub_f32_e32 v2, v6, v1
	v_exp_f32_e32 v52, v2
	v_sub_f32_e32 v2, v54, v1
	v_exp_f32_e32 v154, v2
	v_add_f32_e32 v53, v51, v119
	v_mul_f32_e32 v4, v20, v150
	v_mul_f32_e32 v5, v21, v150
	v_mul_f32_e32 v20, v36, v150
	v_mul_f32_e32 v21, v37, v150
	v_add_f32_e32 v2, v52, v154
	v_add_f32_e32 v3, v53, v155
	s_nop 0
	v_add_f32_e32 v156, v2, v2
	v_add_f32_e32 v157, v2, v3
	v_sub_f32_e32 v2, v7, v1
	v_exp_f32_e32 v53, v2
	v_sub_f32_e32 v2, v55, v1
	v_exp_f32_e32 v121, v2
	v_sub_f32_e32 v2, v8, v1
	v_exp_f32_e32 v54, v2
	v_sub_f32_e32 v2, v56, v1
	v_exp_f32_e32 v156, v2
	v_add_f32_e32 v55, v53, v121
	v_mul_f32_e32 v6, v22, v150
	v_mul_f32_e32 v7, v23, v150
	v_mul_f32_e32 v22, v38, v150
	v_mul_f32_e32 v23, v39, v150
	v_add_f32_e32 v2, v54, v156
	v_add_f32_e32 v3, v55, v157
	v_cvt_pk_bf16_f32 v38, v113, v117
	v_add_f32_e32 v158, v2, v2
	v_add_f32_e32 v159, v2, v3
	v_sub_f32_e32 v2, v9, v1
	v_exp_f32_e32 v55, v2
	v_sub_f32_e32 v2, v57, v1
	v_exp_f32_e32 v123, v2
	v_sub_f32_e32 v2, v10, v1
	v_exp_f32_e32 v56, v2
	v_sub_f32_e32 v2, v58, v1
	v_exp_f32_e32 v158, v2
	v_add_f32_e32 v57, v55, v123
	v_mul_f32_e32 v8, v24, v150
	v_mul_f32_e32 v9, v25, v150
	v_mul_f32_e32 v24, v40, v150
	v_mul_f32_e32 v25, v41, v150
	v_add_f32_e32 v2, v56, v158
	v_add_f32_e32 v3, v57, v159
	v_cvt_pk_bf16_f32 v39, v152, v119
	v_add_f32_e32 v164, v2, v2
	v_add_f32_e32 v165, v2, v3
	v_sub_f32_e32 v2, v11, v1
	v_exp_f32_e32 v57, v2
	v_sub_f32_e32 v2, v59, v1
	v_exp_f32_e32 v125, v2
	v_sub_f32_e32 v2, v12, v1
	v_exp_f32_e32 v58, v2
	v_sub_f32_e32 v2, v60, v1
	v_exp_f32_e32 v164, v2
	v_add_f32_e32 v59, v57, v125
	v_mul_f32_e32 v10, v26, v150
	v_mul_f32_e32 v11, v27, v150
	v_mul_f32_e32 v26, v42, v150
	v_mul_f32_e32 v27, v43, v150
	v_add_f32_e32 v2, v58, v164
	v_add_f32_e32 v3, v59, v165
	v_cvt_pk_bf16_f32 v42, v56, v57
	v_add_f32_e32 v166, v2, v2
	v_add_f32_e32 v167, v2, v3
	v_sub_f32_e32 v2, v13, v1
	v_exp_f32_e32 v59, v2
	v_sub_f32_e32 v2, v61, v1
	v_exp_f32_e32 v127, v2
	v_sub_f32_e32 v2, v14, v1
	v_exp_f32_e32 v60, v2
	v_sub_f32_e32 v2, v62, v1
	v_exp_f32_e32 v166, v2
	v_add_f32_e32 v61, v59, v127
	v_mul_f32_e32 v12, v28, v150
	v_mul_f32_e32 v13, v29, v150
	v_mul_f32_e32 v28, v44, v150
	v_mul_f32_e32 v29, v45, v150
	v_add_f32_e32 v2, v60, v166
	v_add_f32_e32 v3, v61, v167
	v_cvt_pk_bf16_f32 v43, v58, v59
	v_add_f32_e32 v168, v2, v2
	v_add_f32_e32 v169, v2, v3
	v_sub_f32_e32 v2, v15, v1
	v_exp_f32_e32 v61, v2
	v_sub_f32_e32 v2, v63, v1
	v_exp_f32_e32 v129, v2
	v_sub_f32_e32 v2, v16, v1
	v_exp_f32_e32 v62, v2
	v_sub_f32_e32 v2, v64, v1
	v_exp_f32_e32 v168, v2
	v_sub_f32_e32 v2, v17, v1
	v_mul_f32_e32 v16, v32, v150
	v_mul_f32_e32 v17, v33, v150
	v_mul_f32_e32 v14, v30, v150
	v_mul_f32_e32 v15, v31, v150
	v_mul_f32_e32 v32, v48, v150
	v_mul_f32_e32 v33, v49, v150
	v_mul_f32_e32 v30, v46, v150
	v_mul_f32_e32 v31, v47, v150
	v_cvt_pk_bf16_f32 v47, v50, v51
	v_cvt_pk_bf16_f32 v48, v52, v53
	ds_read_b128 v[50:53], v163 offset:24576
	v_add_f32_e32 v63, v61, v129
	v_add_f32_e32 v148, v62, v168
	v_add_f32_e32 v149, v63, v169
	v_exp_f32_e32 v63, v2
	v_sub_f32_e32 v2, v65, v1
	v_exp_f32_e32 v64, v2
	v_mul_f32_e32 v2, v18, v150
	v_mul_f32_e32 v3, v19, v150
	v_cvt_pk_bf16_f32 v46, v111, v115
	v_cvt_pk_bf16_f32 v49, v54, v55
	v_mul_f32_e32 v18, v34, v150
	v_mul_f32_e32 v19, v35, v150
	v_cvt_pk_bf16_f32 v44, v60, v61
	s_waitcnt lgkmcnt(0)
	v_mfma_f32_32x32x16_bf16 v[2:17], v[50:53], v[46:49], v[2:17]
	ds_read_b128 v[50:53], v163 offset:28672
	v_cvt_pk_bf16_f32 v45, v62, v63
	v_cvt_pk_bf16_f32 v40, v154, v121
	v_cvt_pk_bf16_f32 v41, v156, v123
	v_cvt_pk_bf16_f32 v34, v158, v125
	v_cvt_pk_bf16_f32 v35, v164, v127
	v_cvt_pk_bf16_f32 v36, v166, v129
	s_waitcnt lgkmcnt(0)
	v_mfma_f32_32x32x16_bf16 v[18:33], v[50:53], v[46:49], v[18:33]
	ds_read_b128 v[46:49], v162 offset:24576
	v_cvt_pk_bf16_f32 v37, v168, v64
	s_waitcnt vmcnt(5)
	ds_write_b128 v204, v[188:191] offset:32768
	s_waitcnt vmcnt(4)
	ds_write_b128 v204, v[192:195] offset:40960
	s_waitcnt lgkmcnt(0)
	s_barrier
	ds_read_b128 v[152:155], v105 offset:32768
	ds_read_b128 v[50:53], v103 offset:36864
	v_add_f32_e32 v146, v63, v64
	s_waitcnt lgkmcnt(2)
	v_mfma_f32_32x32x16_bf16 v[2:17], v[46:49], v[42:45], v[2:17]
	ds_read_b128 v[46:49], v162 offset:28672
	s_waitcnt lgkmcnt(0)
	v_mfma_f32_32x32x16_bf16 v[18:33], v[46:49], v[42:45], v[18:33]
	ds_read_b128 v[42:45], v161 offset:24576
	s_waitcnt lgkmcnt(0)
	v_mfma_f32_32x32x16_bf16 v[2:17], v[42:45], v[38:41], v[2:17]
	ds_read_b128 v[42:45], v161 offset:28672
	s_waitcnt lgkmcnt(0)
	v_mfma_f32_32x32x16_bf16 v[18:33], v[42:45], v[38:41], v[18:33]
	global_load_dwordx4 v[70:73], v[178:179], off offset:64
	ds_read_b128 v[38:41], v160 offset:24576
	s_waitcnt lgkmcnt(0)
	v_mfma_f32_32x32x16_bf16 v[2:17], v[38:41], v[34:37], v[2:17]
	ds_read_b128 v[38:41], v160 offset:28672
	s_waitcnt lgkmcnt(0)
	v_mfma_f32_32x32x16_bf16 v[18:33], v[38:41], v[34:37], v[18:33]
	ds_read_b128 v[34:37], v103 offset:32768
	s_waitcnt lgkmcnt(0)
	v_mfma_f32_32x32x16_bf16 v[34:49], v[34:37], v[94:97], 0
	v_mfma_f32_32x32x16_bf16 v[34:49], v[152:155], v[90:93], v[34:49]
	ds_read_b128 v[152:155], v105 offset:36864
	v_mfma_f32_32x32x16_bf16 v[50:65], v[50:53], v[94:97], 0
	s_waitcnt lgkmcnt(0)
	v_mfma_f32_32x32x16_bf16 v[50:65], v[152:155], v[90:93], v[50:65]
	ds_read_b128 v[152:155], v107 offset:32768
	s_waitcnt lgkmcnt(0)
	v_mfma_f32_32x32x16_bf16 v[34:49], v[152:155], v[86:89], v[34:49]
	ds_read_b128 v[152:155], v107 offset:36864
	s_waitcnt lgkmcnt(0)
	v_mfma_f32_32x32x16_bf16 v[50:65], v[152:155], v[86:89], v[50:65]
	ds_read_b128 v[152:155], v101 offset:32768
	s_waitcnt lgkmcnt(0)
	v_mfma_f32_32x32x16_bf16 v[34:49], v[152:155], v[82:85], v[34:49]
	ds_read_b128 v[152:155], v101 offset:36864
	s_waitcnt lgkmcnt(0)
	v_mfma_f32_32x32x16_bf16 v[50:65], v[152:155], v[82:85], v[50:65]
	s_nop 8
	v_max_f32_e32 v109, v35, v35
	v_max_f32_e32 v111, v34, v34
	v_max_f32_e32 v109, v111, v109
	v_max3_f32 v109, v109, v36, v37
	v_max3_f32 v109, v109, v38, v39
	v_max3_f32 v109, v109, v40, v41
	v_max3_f32 v109, v109, v42, v43
	v_max3_f32 v109, v109, v44, v45
	v_max3_f32 v109, v109, v46, v47
	v_max3_f32 v109, v109, v48, v49
	v_max3_f32 v109, v109, v50, v51
	v_max3_f32 v109, v109, v52, v53
	v_max3_f32 v109, v109, v54, v55
	v_max3_f32 v109, v109, v56, v57
	v_max3_f32 v109, v109, v58, v59
	v_max3_f32 v109, v109, v60, v61
	v_max3_f32 v109, v109, v62, v63
	v_max3_f32 v109, v109, v64, v65
	v_mov_b32_e32 v111, v109
	s_nop 1
	v_permlane32_swap_b32_e32 v109, v111
	v_max3_f32 v109, v1, v109, v111
	v_sub_f32_e32 v34, v34, v109
	v_exp_f32_e32 v111, v34
	v_sub_f32_e32 v34, v50, v109
	v_exp_f32_e32 v113, v34
	v_sub_f32_e32 v1, v1, v109
	v_exp_f32_e32 v156, v1
	v_add_f32_e32 v34, v111, v113
	v_add_f32_e32 v159, 0, v34
	v_sub_f32_e32 v34, v35, v109
	v_exp_f32_e32 v115, v34
	v_sub_f32_e32 v34, v51, v109
	v_exp_f32_e32 v117, v34
	v_sub_f32_e32 v34, v36, v109
	v_sub_f32_e32 v36, v52, v109
	v_exp_f32_e32 v34, v34
	v_exp_f32_e32 v158, v36
	v_add_f32_e32 v35, v115, v117
	v_sub_f32_e32 v36, v53, v109
	v_exp_f32_e32 v119, v36
	v_add_f32_e32 v50, v34, v158
	v_add_f32_e32 v51, v35, v159
	v_sub_f32_e32 v35, v37, v109
	v_add_f32_e32 v51, v50, v51
	v_add_f32_e32 v50, v50, v50
	v_exp_f32_e32 v35, v35
	v_sub_f32_e32 v36, v38, v109
	v_sub_f32_e32 v38, v54, v109
	v_exp_f32_e32 v36, v36
	v_exp_f32_e32 v50, v38
	v_add_f32_e32 v37, v35, v119
	v_sub_f32_e32 v38, v55, v109
	v_mul_f32_e32 v16, v16, v156
	v_mul_f32_e32 v17, v17, v156
	v_add_f32_e32 v52, v36, v50
	v_add_f32_e32 v53, v37, v51
	v_sub_f32_e32 v37, v39, v109
	v_add_f32_e32 v53, v52, v53
	v_add_f32_e32 v52, v52, v52
	v_exp_f32_e32 v37, v37
	v_exp_f32_e32 v51, v38
	v_sub_f32_e32 v38, v40, v109
	v_sub_f32_e32 v40, v56, v109
	v_exp_f32_e32 v38, v38
	v_exp_f32_e32 v52, v40
	v_add_f32_e32 v39, v37, v51
	v_sub_f32_e32 v40, v57, v109
	v_mul_f32_e32 v14, v14, v156
	v_mul_f32_e32 v15, v15, v156
	v_add_f32_e32 v54, v38, v52
	v_add_f32_e32 v55, v39, v53
	v_sub_f32_e32 v39, v41, v109
	v_add_f32_e32 v55, v54, v55
	v_add_f32_e32 v54, v54, v54
	v_exp_f32_e32 v39, v39
	v_exp_f32_e32 v53, v40
	v_sub_f32_e32 v40, v42, v109
	v_sub_f32_e32 v42, v58, v109
	v_exp_f32_e32 v40, v40
	v_exp_f32_e32 v54, v42
	v_add_f32_e32 v41, v39, v53
	v_sub_f32_e32 v42, v59, v109
	v_mul_f32_e32 v12, v12, v156
	v_mul_f32_e32 v13, v13, v156
	v_add_f32_e32 v56, v40, v54
	v_add_f32_e32 v57, v41, v55
	v_sub_f32_e32 v41, v43, v109
	v_exp_f32_e32 v55, v42
	v_sub_f32_e32 v42, v44, v109
	v_add_f32_e32 v57, v56, v57
	v_add_f32_e32 v56, v56, v56
	v_exp_f32_e32 v41, v41
	v_exp_f32_e32 v58, v42
	v_sub_f32_e32 v42, v60, v109
	v_exp_f32_e32 v56, v42
	v_add_f32_e32 v59, v41, v55
	v_mul_f32_e32 v10, v10, v156
	v_mul_f32_e32 v11, v11, v156
	v_mul_f32_e32 v8, v8, v156
	v_mul_f32_e32 v9, v9, v156
	v_add_f32_e32 v42, v58, v56
	v_add_f32_e32 v43, v59, v57
	v_mul_f32_e32 v6, v6, v156
	v_mul_f32_e32 v7, v7, v156
	v_add_f32_e32 v164, v42, v42
	v_add_f32_e32 v165, v42, v43
	v_sub_f32_e32 v42, v45, v109
	v_exp_f32_e32 v57, v42
	v_sub_f32_e32 v42, v61, v109
	v_exp_f32_e32 v59, v42
	v_sub_f32_e32 v42, v46, v109
	v_exp_f32_e32 v44, v42
	v_sub_f32_e32 v42, v62, v109
	v_exp_f32_e32 v164, v42
	v_add_f32_e32 v45, v57, v59
	v_mul_f32_e32 v4, v4, v156
	v_mul_f32_e32 v5, v5, v156
	v_mul_f32_e32 v2, v2, v156
	v_mul_f32_e32 v3, v3, v156
	v_add_f32_e32 v42, v44, v164
	v_add_f32_e32 v43, v45, v165
	v_cvt_pk_bf16_f32 v46, v111, v115
	v_add_f32_e32 v60, v42, v42
	v_add_f32_e32 v61, v42, v43
	v_sub_f32_e32 v42, v47, v109
	v_exp_f32_e32 v45, v42
	v_sub_f32_e32 v42, v63, v109
	v_exp_f32_e32 v121, v42
	v_sub_f32_e32 v42, v48, v109
	v_exp_f32_e32 v62, v42
	v_sub_f32_e32 v42, v64, v109
	v_exp_f32_e32 v60, v42
	v_add_f32_e32 v63, v45, v121
	v_sub_f32_e32 v42, v49, v109
	v_cvt_pk_bf16_f32 v47, v34, v35
	v_add_f32_e32 v154, v62, v60
	v_add_f32_e32 v155, v63, v61
	v_exp_f32_e32 v61, v42
	v_sub_f32_e32 v42, v65, v109
	v_exp_f32_e32 v63, v42
	v_cvt_pk_bf16_f32 v42, v40, v41
	v_cvt_pk_bf16_f32 v40, v50, v51
	v_cvt_pk_bf16_f32 v41, v52, v53
	ds_read_b128 v[50:53], v163 offset:40960
	v_cvt_pk_bf16_f32 v48, v36, v37
	v_cvt_pk_bf16_f32 v49, v38, v39
	v_mul_f32_e32 v32, v32, v156
	v_mul_f32_e32 v33, v33, v156
	v_mul_f32_e32 v30, v30, v156
	v_mul_f32_e32 v31, v31, v156
	s_waitcnt lgkmcnt(0)
	v_mfma_f32_32x32x16_bf16 v[2:17], v[50:53], v[46:49], v[2:17]
	ds_read_b128 v[50:53], v163 offset:45056
	v_mul_f32_e64 v28, v28, v156
	v_mul_f32_e64 v29, v29, v156
	v_mul_f32_e64 v26, v26, v156
	v_mul_f32_e64 v27, v27, v156
	v_mul_f32_e32 v24, v24, v156
	v_mul_f32_e32 v25, v25, v156
	v_mul_f32_e32 v22, v22, v156
	v_mul_f32_e32 v23, v23, v156
	v_mul_f32_e32 v20, v20, v156
	v_mul_f32_e32 v21, v21, v156
	v_mul_f32_e32 v18, v18, v156
	v_mul_f32_e32 v19, v19, v156
	v_cvt_pk_bf16_f32 v43, v58, v57
	v_cvt_pk_bf16_f32 v44, v44, v45
	s_waitcnt lgkmcnt(0)
	v_mfma_f32_32x32x16_bf16 v[18:33], v[50:53], v[46:49], v[18:33]
	ds_read_b128 v[46:49], v162 offset:40960
	v_cvt_pk_bf16_f32 v45, v62, v61
	v_cvt_pk_bf16_f32 v38, v113, v117
	v_cvt_pk_bf16_f32 v39, v158, v119
	v_cvt_pk_bf16_f32 v34, v54, v55
	v_cvt_pk_bf16_f32 v35, v56, v59
	v_cvt_pk_bf16_f32 v36, v164, v121
	s_waitcnt lgkmcnt(0)
	v_mfma_f32_32x32x16_bf16 v[2:17], v[46:49], v[42:45], v[2:17]
	ds_read_b128 v[46:49], v162 offset:45056
	v_cvt_pk_bf16_f32 v37, v60, v63
	s_waitcnt vmcnt(4)
	ds_write_b128 v204, v[196:199] offset:49152
	s_waitcnt vmcnt(3)
	ds_write_b128 v204, v[200:203] offset:57344
	s_waitcnt lgkmcnt(0)
	s_barrier
	ds_read_b128 v[50:53], v103 offset:53248
	v_add_f32_e32 v152, v61, v63
	s_waitcnt lgkmcnt(1)
	v_mfma_f32_32x32x16_bf16 v[18:33], v[46:49], v[42:45], v[18:33]
	ds_read_b128 v[42:45], v161 offset:40960
	s_waitcnt lgkmcnt(0)
	v_mfma_f32_32x32x16_bf16 v[2:17], v[42:45], v[38:41], v[2:17]
	ds_read_b128 v[42:45], v161 offset:45056
	s_waitcnt lgkmcnt(0)
	v_mfma_f32_32x32x16_bf16 v[18:33], v[42:45], v[38:41], v[18:33]
	global_load_dwordx4 v[66:69], v[178:179], off offset:96
	ds_read_b128 v[38:41], v160 offset:40960
	s_waitcnt lgkmcnt(0)
	v_mfma_f32_32x32x16_bf16 v[2:17], v[38:41], v[34:37], v[2:17]
	ds_read_b128 v[38:41], v160 offset:45056
	s_waitcnt lgkmcnt(0)
	v_mfma_f32_32x32x16_bf16 v[18:33], v[38:41], v[34:37], v[18:33]
	ds_read_b128 v[34:37], v103 offset:49152
	s_waitcnt lgkmcnt(0)
	v_mfma_f32_32x32x16_bf16 v[34:49], v[34:37], v[94:97], 0
	v_mfma_f32_32x32x16_bf16 v[50:65], v[50:53], v[94:97], 0
	ds_read_b128 v[94:97], v105 offset:49152
	s_waitcnt lgkmcnt(0)
	v_mfma_f32_32x32x16_bf16 v[34:49], v[94:97], v[90:93], v[34:49]
	ds_read_b128 v[94:97], v105 offset:53248
	s_waitcnt lgkmcnt(0)
	v_mfma_f32_32x32x16_bf16 v[50:65], v[94:97], v[90:93], v[50:65]
	ds_read_b128 v[90:93], v107 offset:49152
	s_waitcnt lgkmcnt(0)
	v_mfma_f32_32x32x16_bf16 v[34:49], v[90:93], v[86:89], v[34:49]
	ds_read_b128 v[90:93], v107 offset:53248
	s_waitcnt lgkmcnt(0)
	v_mfma_f32_32x32x16_bf16 v[50:65], v[90:93], v[86:89], v[50:65]
	ds_read_b128 v[86:89], v101 offset:49152
	s_waitcnt lgkmcnt(0)
	v_mfma_f32_32x32x16_bf16 v[34:49], v[86:89], v[82:85], v[34:49]
	ds_read_b128 v[86:89], v101 offset:53248
	s_waitcnt lgkmcnt(0)
	v_mfma_f32_32x32x16_bf16 v[50:65], v[86:89], v[82:85], v[50:65]
	s_nop 8
	v_max_f32_e32 v1, v35, v35
	v_max_f32_e32 v82, v34, v34
	v_max_f32_e32 v1, v82, v1
	v_max3_f32 v1, v1, v36, v37
	v_max3_f32 v1, v1, v38, v39
	v_max3_f32 v1, v1, v40, v41
	v_max3_f32 v1, v1, v42, v43
	v_max3_f32 v1, v1, v44, v45
	v_max3_f32 v1, v1, v46, v47
	v_max3_f32 v1, v1, v48, v49
	v_max3_f32 v1, v1, v50, v51
	v_max3_f32 v1, v1, v52, v53
	v_max3_f32 v1, v1, v54, v55
	v_max3_f32 v1, v1, v56, v57
	v_max3_f32 v1, v1, v58, v59
	v_max3_f32 v1, v1, v60, v61
	v_max3_f32 v1, v1, v62, v63
	v_max3_f32 v1, v1, v64, v65
	v_mov_b32_e32 v82, v1
	s_nop 1
	v_permlane32_swap_b32_e32 v1, v82
	v_max3_f32 v82, v109, v1, v82
	v_sub_f32_e32 v1, v34, v82
	v_exp_f32_e32 v105, v1
	v_sub_f32_e32 v1, v50, v82
	v_exp_f32_e32 v101, v1
	v_sub_f32_e32 v1, v35, v82
	v_sub_f32_e32 v83, v109, v82
	v_exp_f32_e32 v109, v1
	v_sub_f32_e32 v1, v51, v82
	v_exp_f32_e32 v103, v1
	v_sub_f32_e32 v1, v36, v82
	v_exp_f32_e32 v113, v1
	v_sub_f32_e32 v1, v52, v82
	v_exp_f32_e32 v107, v1
	v_sub_f32_e32 v1, v37, v82
	v_exp_f32_e32 v117, v1
	v_sub_f32_e32 v1, v53, v82
	v_exp_f32_e32 v111, v1
	v_sub_f32_e32 v1, v38, v82
	v_exp_f32_e32 v121, v1
	v_sub_f32_e32 v1, v54, v82
	v_exp_f32_e32 v115, v1
	v_sub_f32_e32 v1, v39, v82
	v_exp_f32_e32 v123, v1
	v_sub_f32_e32 v1, v55, v82
	v_exp_f32_e32 v119, v1
	v_sub_f32_e32 v1, v40, v82
	v_exp_f32_e32 v129, v1
	v_sub_f32_e32 v1, v56, v82
	v_exp_f32_e32 v125, v1
	v_sub_f32_e32 v1, v41, v82
	v_exp_f32_e32 v133, v1
	v_sub_f32_e32 v1, v57, v82
	v_exp_f32_e32 v127, v1
	v_sub_f32_e32 v1, v42, v82
	v_add_f32_e32 v34, v104, v100
	v_add_f32_e32 v35, v105, v101
	v_exp_f32_e32 v137, v1
	v_sub_f32_e32 v1, v58, v82
	v_add_f32_e32 v34, v34, v144
	v_add_f32_e32 v35, v35, v145
	v_add_f32_e32 v36, v108, v102
	v_add_f32_e32 v37, v109, v103
	v_exp_f32_e32 v131, v1
	v_sub_f32_e32 v1, v43, v82
	v_add_f32_e32 v34, v36, v34
	v_add_f32_e32 v35, v37, v35
	v_add_f32_e32 v36, v112, v106
	v_add_f32_e32 v37, v113, v107
	v_exp_f32_e32 v141, v1
	v_sub_f32_e32 v1, v59, v82
	v_add_f32_e32 v34, v36, v34
	v_add_f32_e32 v35, v37, v35
	v_add_f32_e32 v36, v116, v110
	v_add_f32_e32 v37, v117, v111
	v_exp_f32_e32 v135, v1
	v_sub_f32_e32 v1, v44, v82
	v_add_f32_e32 v34, v36, v34
	v_add_f32_e32 v35, v37, v35
	v_add_f32_e32 v36, v120, v114
	v_add_f32_e32 v37, v121, v115
	v_exp_f32_e32 v143, v1
	v_sub_f32_e32 v1, v60, v82
	v_exp_f32_e32 v139, v1
	v_sub_f32_e32 v1, v45, v82
	v_add_f32_e32 v34, v36, v34
	v_add_f32_e32 v35, v37, v35
	v_add_f32_e32 v36, v122, v118
	v_add_f32_e32 v37, v123, v119
	v_exp_f32_e32 v53, v1
	v_sub_f32_e32 v1, v61, v82
	v_sub_f32_e32 v38, v46, v82
	v_add_f32_e32 v34, v36, v34
	v_add_f32_e32 v35, v37, v35
	v_add_f32_e32 v36, v128, v124
	v_add_f32_e32 v37, v129, v125
	v_exp_f32_e32 v54, v1
	v_exp_f32_e32 v55, v38
	v_sub_f32_e32 v38, v62, v82
	v_add_f32_e32 v34, v36, v34
	v_add_f32_e32 v35, v37, v35
	v_add_f32_e32 v36, v132, v126
	v_add_f32_e32 v37, v133, v127
	v_exp_f32_e32 v56, v38
	v_add_f32_e32 v34, v36, v34
	v_add_f32_e32 v35, v37, v35
	v_add_f32_e32 v36, v136, v130
	v_add_f32_e32 v37, v137, v131
	v_sub_f32_e32 v38, v47, v82
	v_add_f32_e32 v34, v36, v34
	v_add_f32_e32 v35, v37, v35
	v_add_f32_e32 v36, v140, v134
	v_add_f32_e32 v37, v141, v135
	v_exp_f32_e32 v147, v38
	v_sub_f32_e32 v38, v63, v82
	v_add_f32_e32 v34, v36, v34
	v_add_f32_e32 v35, v37, v35
	v_add_f32_e32 v36, v142, v138
	v_add_f32_e32 v37, v143, v139
	v_add_f32_e32 v1, v53, v54
	v_exp_f32_e32 v57, v38
	v_sub_f32_e32 v38, v48, v82
	v_add_f32_e32 v34, v36, v34
	v_add_f32_e32 v35, v37, v35
	v_add_f32_e32 v151, v55, v56
	v_exp_f32_e32 v58, v38
	v_sub_f32_e32 v38, v64, v82
	v_add_f32_e32 v0, v0, v34
	v_add_f32_e32 v1, v1, v35
	v_exp_f32_e32 v59, v38
	v_mul_f32_e32 v34, v0, v150
	v_mul_f32_e32 v35, v1, v151
	v_add_f32_e32 v0, v0, v150
	v_add_f32_e32 v1, v1, v151
	v_sub_f32_e32 v38, v49, v82
	v_mov_b32_e32 v35, v1
	v_add_f32_e32 v0, v148, v149
	v_add_f32_e32 v1, v149, v148
	v_exp_f32_e32 v153, v38
	v_sub_f32_e32 v38, v65, v82
	v_mov_b32_e32 v1, v57
	v_exp_f32_e32 v60, v38
	v_add_f32_e32 v0, v146, v0
	v_add_f32_e32 v1, v147, v1
	v_add_f32_e32 v157, v58, v59
	v_add_f32_e32 v0, v34, v0
	v_add_f32_e32 v1, v35, v1
	v_exp_f32_e32 v52, v83
	v_mul_f32_e32 v34, v0, v156
	v_mul_f32_e32 v35, v1, v157
	v_add_f32_e32 v0, v0, v156
	v_add_f32_e32 v1, v1, v157
	v_mul_f32_e32 v48, v16, v52
	v_mul_f32_e32 v49, v17, v52
	v_mov_b32_e32 v35, v1
	v_add_f32_e32 v0, v154, v155
	v_add_f32_e32 v1, v155, v154
	v_mul_f32_e32 v40, v8, v52
	v_mul_f32_e32 v41, v9, v52
	v_mov_b32_e32 v1, v60
	v_add_f32_e32 v0, v152, v0
	v_add_f32_e32 v1, v153, v1
	v_mul_f32_e32 v8, v26, v52
	v_mul_f32_e32 v9, v27, v52
	v_add_f32_e32 v50, v34, v0
	v_add_f32_e32 v51, v35, v1
	v_mul_f32_e32 v0, v18, v52
	v_mul_f32_e32 v1, v19, v52
	v_cvt_pk_bf16_f32 v26, v55, v147
	v_cvt_pk_bf16_f32 v17, v139, v54
	v_cvt_pk_bf16_f32 v18, v56, v57
	ds_read_b128 v[54:57], v163 offset:57344
	v_mul_f32_e32 v46, v14, v52
	v_mul_f32_e32 v47, v15, v52
	v_mul_f32_e32 v44, v12, v52
	v_mul_f32_e32 v45, v13, v52
	v_mul_f32_e32 v42, v10, v52
	v_mul_f32_e32 v43, v11, v52
	v_mul_f32_e32 v38, v6, v52
	v_mul_f32_e32 v39, v7, v52
	v_mul_f32_e32 v36, v4, v52
	v_mul_f32_e32 v37, v5, v52
	v_mul_f32_e32 v34, v2, v52
	v_mul_f32_e32 v35, v3, v52
	v_mul_f32_e32 v12, v30, v52
	v_mul_f32_e32 v13, v31, v52
	v_mul_f32_e32 v10, v28, v52
	v_mul_f32_e32 v11, v29, v52
	v_cvt_pk_bf16_f32 v28, v105, v109
	v_cvt_pk_bf16_f32 v29, v113, v117
	v_cvt_pk_bf16_f32 v30, v121, v123
	v_cvt_pk_bf16_f32 v31, v129, v133
	v_mul_f32_e32 v14, v32, v52
	v_mul_f32_e32 v15, v33, v52
	v_mul_f32_e32 v6, v24, v52
	v_mul_f32_e32 v7, v25, v52
	s_waitcnt lgkmcnt(0)
	v_mfma_f32_32x32x16_bf16 v[34:49], v[54:57], v[28:31], v[34:49]
	ds_read_b128 v[54:57], v163 offset:61440
	v_mul_f32_e64 v4, v22, v52
	v_mul_f32_e64 v5, v23, v52
	v_mul_f32_e64 v2, v20, v52
	v_mul_f32_e64 v3, v21, v52
	v_cvt_pk_bf16_f32 v24, v137, v141
	v_cvt_pk_bf16_f32 v25, v143, v53
	v_cvt_pk_bf16_f32 v27, v58, v153
	v_cvt_pk_bf16_f32 v20, v101, v103
	s_waitcnt lgkmcnt(0)
	v_mfma_f32_32x32x16_bf16 v[0:15], v[54:57], v[28:31], v[0:15]
	ds_read_b128 v[28:31], v162 offset:57344
	v_cvt_pk_bf16_f32 v21, v107, v111
	v_cvt_pk_bf16_f32 v22, v115, v119
	v_cvt_pk_bf16_f32 v23, v125, v127
	v_cvt_pk_bf16_f32 v16, v131, v135
	v_cvt_pk_bf16_f32 v19, v59, v60
	v_fmac_f32_e32 v51, v50, v52
	s_waitcnt lgkmcnt(0)
	v_mfma_f32_32x32x16_bf16 v[34:49], v[28:31], v[24:27], v[34:49]
	ds_read_b128 v[28:31], v162 offset:61440
	s_waitcnt lgkmcnt(0)
	v_mfma_f32_32x32x16_bf16 v[0:15], v[28:31], v[24:27], v[0:15]
	ds_read_b128 v[24:27], v161 offset:57344
	s_waitcnt lgkmcnt(0)
	v_mfma_f32_32x32x16_bf16 v[34:49], v[24:27], v[20:23], v[34:49]
	ds_read_b128 v[24:27], v161 offset:61440
	s_waitcnt lgkmcnt(0)
	v_mfma_f32_32x32x16_bf16 v[0:15], v[24:27], v[20:23], v[0:15]
	ds_read_b128 v[20:23], v160 offset:57344
	s_waitcnt vmcnt(3)
	v_mov_b32_e32 v26, v81
	s_nop 1
	v_permlane32_swap_b32_e32 v79, v26
	s_waitcnt lgkmcnt(0)
	v_mfma_f32_32x32x16_bf16 v[34:49], v[20:23], v[16:19], v[34:49]
	ds_read_b128 v[20:23], v160 offset:61440
	s_waitcnt lgkmcnt(0)
	v_mfma_f32_32x32x16_bf16 v[0:15], v[20:23], v[16:19], v[0:15]
	v_mov_b32_e32 v16, v51
	s_nop 1
	v_permlane32_swap_b32_e32 v51, v16
	v_add_f32_e32 v16, v51, v16
	v_div_scale_f32 v17, s[2:3], v16, v16, 1.0
	v_rcp_f32_e32 v18, v17
	s_nop 0
	v_fma_f32 v19, -v17, v18, 1.0
	v_fmac_f32_e32 v18, v19, v18
	v_div_scale_f32 v19, vcc, 1.0, v16, 1.0
	v_mul_f32_e32 v20, v19, v18
	v_fma_f32 v21, -v17, v20, v19
	v_fmac_f32_e32 v20, v21, v18
	v_fma_f32 v17, -v17, v20, v19
	v_div_fmas_f32 v17, v17, v18, v20
	v_div_fixup_f32 v20, v17, v16, 1.0
	v_lshlrev_b64 v[16:17], 11, v[98:99]
	v_mov_b32_e32 v21, v80
	v_lshl_add_u64 v[16:17], s[0:1], 0, v[16:17]
	s_nop 0
	v_permlane32_swap_b32_e32 v78, v21
	v_lshl_add_u64 v[22:23], v[16:17], 0, v[176:177]
	v_lshlrev_b32_e32 v16, 16, v78
	v_and_b32_e32 v17, 0xffff0000, v78
	v_mul_f32_e32 v18, v34, v20
	v_mul_f32_e32 v19, v35, v20
	v_mul_f32_e32 v24, v36, v20
	v_mul_f32_e32 v25, v37, v20
	v_mul_f32_e32 v16, v18, v16
	v_mul_f32_e32 v17, v19, v17
	v_lshlrev_b32_e32 v18, 16, v79
	v_and_b32_e32 v19, 0xffff0000, v79
	v_mul_f32_e32 v18, v24, v18
	v_mul_f32_e32 v19, v25, v19
	v_cvt_pk_bf16_f32 v16, v16, v17
	v_cvt_pk_bf16_f32 v17, v18, v19
	v_lshlrev_b32_e32 v18, 16, v21
	v_and_b32_e32 v19, 0xffff0000, v21
	v_mul_f32_e32 v24, v38, v20
	v_mul_f32_e32 v25, v39, v20
	s_nop 0
	v_mul_f32_e32 v18, v24, v18
	v_mul_f32_e32 v19, v25, v19
	v_lshlrev_b32_e32 v24, 16, v26
	v_and_b32_e32 v25, 0xffff0000, v26
	v_mul_f32_e32 v26, v40, v20
	v_mul_f32_e32 v27, v41, v20
	v_cvt_pk_bf16_f32 v18, v18, v19
	v_mul_f32_e32 v24, v26, v24
	v_mul_f32_e32 v25, v27, v25
	s_waitcnt vmcnt(2)
	v_mov_b32_e32 v21, v76
	v_cvt_pk_bf16_f32 v19, v24, v25
	v_permlane32_swap_b32_e32 v16, v18
	s_nop 0
	v_permlane32_swap_b32_e32 v17, v19
	v_permlane32_swap_b32_e32 v74, v21
	v_mov_b32_e32 v26, v77
	global_store_dwordx4 v[22:23], v[16:19], off offset:1536
	s_nop 0
	v_permlane32_swap_b32_e32 v75, v26
	v_lshlrev_b32_e32 v16, 16, v74
	v_and_b32_e32 v17, 0xffff0000, v74
	v_mul_f32_e32 v18, v42, v20
	v_mul_f32_e32 v19, v43, v20
	v_mul_f32_e32 v24, v44, v20
	v_mul_f32_e32 v25, v45, v20
	v_mul_f32_e32 v16, v18, v16
	v_mul_f32_e32 v17, v19, v17
	v_lshlrev_b32_e32 v18, 16, v75
	v_and_b32_e32 v19, 0xffff0000, v75
	v_mul_f32_e32 v18, v24, v18
	v_mul_f32_e32 v19, v25, v19
	v_cvt_pk_bf16_f32 v16, v16, v17
	v_cvt_pk_bf16_f32 v17, v18, v19
	v_lshlrev_b32_e32 v18, 16, v21
	v_and_b32_e32 v19, 0xffff0000, v21
	v_mul_f32_e32 v24, v46, v20
	v_mul_f32_e32 v25, v47, v20
	v_mul_f32_e32 v0, v0, v20
	v_mul_f32_e32 v1, v1, v20
	v_mul_f32_e32 v18, v24, v18
	v_mul_f32_e32 v19, v25, v19
	v_lshlrev_b32_e32 v24, 16, v26
	v_and_b32_e32 v25, 0xffff0000, v26
	v_mul_f32_e32 v26, v48, v20
	v_mul_f32_e32 v27, v49, v20
	v_cvt_pk_bf16_f32 v18, v18, v19
	v_mul_f32_e32 v24, v26, v24
	v_mul_f32_e32 v25, v27, v25
	s_nop 0
	v_permlane32_swap_b32_e32 v16, v18
	v_cvt_pk_bf16_f32 v19, v24, v25
	s_nop 1
	v_permlane32_swap_b32_e32 v17, v19
	global_store_dwordx4 v[22:23], v[16:19], off offset:1568
	v_mul_f32_e32 v2, v2, v20
	v_mul_f32_e32 v3, v3, v20
	v_mul_f32_e32 v4, v4, v20
	v_mul_f32_e32 v5, v5, v20
	s_waitcnt vmcnt(3)
	v_mov_b32_e32 v18, v72
	s_nop 1
	v_permlane32_swap_b32_e32 v70, v18
	v_mov_b32_e32 v19, v73
	s_nop 1
	v_permlane32_swap_b32_e32 v71, v19
	v_lshlrev_b32_e32 v16, 16, v70
	v_and_b32_e32 v17, 0xffff0000, v70
	v_mul_f32_e32 v0, v0, v16
	v_mul_f32_e32 v1, v1, v17
	v_lshlrev_b32_e32 v16, 16, v71
	v_and_b32_e32 v17, 0xffff0000, v71
	v_mul_f32_e32 v2, v2, v16
	v_mul_f32_e32 v3, v3, v17
	v_cvt_pk_bf16_f32 v0, v0, v1
	v_cvt_pk_bf16_f32 v1, v2, v3
	v_lshlrev_b32_e32 v2, 16, v18
	v_and_b32_e32 v3, 0xffff0000, v18
	v_mul_f32_e32 v2, v4, v2
	v_mul_f32_e32 v3, v5, v3
	v_lshlrev_b32_e32 v4, 16, v19
	v_and_b32_e32 v5, 0xffff0000, v19
	v_mul_f32_e32 v6, v6, v20
	v_mul_f32_e32 v7, v7, v20
	v_cvt_pk_bf16_f32 v2, v2, v3
	v_mul_f32_e32 v4, v6, v4
	v_mul_f32_e32 v5, v7, v5
	s_waitcnt vmcnt(2)
	v_mov_b32_e32 v6, v68
	v_cvt_pk_bf16_f32 v3, v4, v5
	v_permlane32_swap_b32_e32 v0, v2
	s_nop 0
	v_permlane32_swap_b32_e32 v1, v3
	v_permlane32_swap_b32_e32 v66, v6
	v_mov_b32_e32 v7, v69
	global_store_dwordx4 v[22:23], v[0:3], off offset:1600
	s_nop 0
	v_permlane32_swap_b32_e32 v67, v7
	v_lshlrev_b32_e32 v0, 16, v66
	v_and_b32_e32 v1, 0xffff0000, v66
	v_mul_f32_e32 v2, v8, v20
	v_mul_f32_e32 v3, v9, v20
	v_mul_f32_e32 v4, v10, v20
	v_mul_f32_e32 v5, v11, v20
	v_mul_f32_e32 v0, v2, v0
	v_mul_f32_e32 v1, v3, v1
	v_lshlrev_b32_e32 v2, 16, v67
	v_and_b32_e32 v3, 0xffff0000, v67
	v_mul_f32_e32 v2, v4, v2
	v_mul_f32_e32 v3, v5, v3
	v_cvt_pk_bf16_f32 v0, v0, v1
	v_cvt_pk_bf16_f32 v1, v2, v3
	v_lshlrev_b32_e32 v2, 16, v6
	v_and_b32_e32 v3, 0xffff0000, v6
	v_mul_f32_e32 v4, v12, v20
	v_mul_f32_e32 v5, v13, v20
	s_nop 0
	v_mul_f32_e32 v2, v4, v2
	v_mul_f32_e32 v3, v5, v3
	v_lshlrev_b32_e32 v4, 16, v7
	v_and_b32_e32 v5, 0xffff0000, v7
	v_mul_f32_e32 v6, v14, v20
	v_mul_f32_e32 v7, v15, v20
	v_cvt_pk_bf16_f32 v2, v2, v3
	v_mul_f32_e32 v4, v6, v4
	v_mul_f32_e32 v5, v7, v5
	s_nop 0
	v_permlane32_swap_b32_e32 v0, v2
	v_cvt_pk_bf16_f32 v3, v4, v5
	s_nop 1
	v_permlane32_swap_b32_e32 v1, v3
	global_store_dwordx4 v[22:23], v[0:3], off offset:1632
	s_cbranch_scc1 .LBB0_907
